# next-layer part-0 weight conversion moved from P2b to the P5 phase exit (248 workgroups idle there during the second tile round)
# speedup vs baseline: 1.0097x; 1.0097x over previous
.LBB0_373:
	s_or_b64 exec, exec, s[30:31]
	v_readlane_b32 s0, v253, 0
	v_readlane_b32 s1, v253, 1
	s_add_i32 s0, s45, 1
	v_writelane_b32 v255, s0, 29
	s_cmp_lg_u32 s45, 3
	s_cselect_b64 s[4:5], -1, 0
	v_writelane_b32 v255, s1, 30
	v_readlane_b32 s0, v254, 11
	v_readlane_b32 s1, v254, 12
	v_writelane_b32 v255, s4, 31
	s_and_b64 s[0:1], s[0:1], s[4:5]
	v_mov_b32_e32 v26, v170
	v_readlane_b32 s2, v253, 2
	v_readlane_b32 s3, v253, 3
	v_writelane_b32 v255, s5, 32
	s_and_b64 vcc, exec, s[0:1]
	s_waitcnt lgkmcnt(0)
	s_barrier
	s_branch .LBB0_438
	s_mov_b64 s[20:21], exec
	v_readlane_b32 s0, v254, 13
	v_readlane_b32 s23, v255, 29
	v_readlane_b32 s4, v253, 20
	v_readlane_b32 s5, v253, 21
	v_readlane_b32 s6, v253, 30
	v_readlane_b32 s7, v253, 31
	v_readlane_b32 s8, v253, 28
	v_readlane_b32 s9, v253, 29
	s_nop 1
	v_add_u32_e32 v27, s0, v26
	s_mul_hi_u32 s1, s23, 0x1ba0000
	s_mul_i32 s0, s23, 0x1ba0000
	s_add_u32 s4, s4, s0
	s_addc_u32 s5, s5, s1
	s_mul_i32 s0, s23, 0xc0000
	s_add_u32 s6, s6, s0
	s_addc_u32 s7, s7, 0
	s_lshl_b32 s0, s23, 10
	s_add_u32 s8, s8, s0
	s_addc_u32 s9, s9, 0
	v_mov_b32_e32 v38, v27
	v_cmp_gt_u32_e32 vcc, 0x6d000, v38
	s_mov_b64 s[10:11], vcc
	v_lshrrev_b32_e32 v39, 6, v38
	s_mov_b32 s22, 0x12c9fb5
	v_mul_hi_u32 v40, v39, s22
	v_mul_u32_u24_e32 v39, 0xda, v40
	v_lshrrev_b32_e32 v42, 6, v38
	v_sub_u32_e32 v39, v42, v39
	v_bfe_u32 v42, v38, 4, 2
	v_lshl_add_u32 v42, v40, 2, v42
	v_and_b32_e32 v40, 15, v38
	v_lshl_add_u32 v40, v39, 4, v40
	v_mov_b32_e32 v39, v42
	v_mul_u32_u24_e32 v41, 0x37400, v39
	v_lshl_add_u32 v41, v40, 2, v41
	v_lshlrev_b32_e32 v24, 11, v40
	v_lshl_add_u32 v24, v39, 4, v24
	v_add_u32_e32 v24, 0x400000, v24
	s_mov_b64 exec, s[10:11]
	global_load_dword v0, v41, s[4:5]
	v_add_u32_e32 v41, 0x6e80, v41
	global_load_dword v1, v41, s[4:5]
	v_add_u32_e32 v41, 0x6e80, v41
	global_load_dword v2, v41, s[4:5]
	v_add_u32_e32 v41, 0x6e80, v41
	global_load_dword v3, v41, s[4:5]
	v_add_u32_e32 v41, 0x6e80, v41
	global_load_dword v4, v41, s[4:5]
	v_add_u32_e32 v41, 0x6e80, v41
	global_load_dword v5, v41, s[4:5]
	v_add_u32_e32 v41, 0x6e80, v41
	global_load_dword v6, v41, s[4:5]
	v_add_u32_e32 v41, 0x6e80, v41
	global_load_dword v7, v41, s[4:5]
	s_mov_b64 exec, s[20:21]
	s_mul_i32 s0, s76, 1
	v_add_u32_e32 v38, s0, v27
	v_cmp_gt_u32_e32 vcc, 0x6d000, v38
	s_mov_b64 s[12:13], vcc
	v_lshrrev_b32_e32 v39, 6, v38
	s_mov_b32 s22, 0x12c9fb5
	v_mul_hi_u32 v40, v39, s22
	v_mul_u32_u24_e32 v39, 0xda, v40
	v_lshrrev_b32_e32 v42, 6, v38
	v_sub_u32_e32 v39, v42, v39
	v_bfe_u32 v42, v38, 4, 2
	v_lshl_add_u32 v42, v40, 2, v42
	v_and_b32_e32 v40, 15, v38
	v_lshl_add_u32 v40, v39, 4, v40
	v_mov_b32_e32 v39, v42
	v_mul_u32_u24_e32 v41, 0x37400, v39
	v_lshl_add_u32 v41, v40, 2, v41
	v_lshlrev_b32_e32 v25, 11, v40
	v_lshl_add_u32 v25, v39, 4, v25
	v_add_u32_e32 v25, 0x400000, v25
	s_mov_b64 exec, s[12:13]
	global_load_dword v8, v41, s[4:5]
	v_add_u32_e32 v41, 0x6e80, v41
	global_load_dword v9, v41, s[4:5]
	v_add_u32_e32 v41, 0x6e80, v41
	global_load_dword v10, v41, s[4:5]
	v_add_u32_e32 v41, 0x6e80, v41
	global_load_dword v11, v41, s[4:5]
	v_add_u32_e32 v41, 0x6e80, v41
	global_load_dword v12, v41, s[4:5]
	v_add_u32_e32 v41, 0x6e80, v41
	global_load_dword v13, v41, s[4:5]
	v_add_u32_e32 v41, 0x6e80, v41
	global_load_dword v14, v41, s[4:5]
	v_add_u32_e32 v41, 0x6e80, v41
	global_load_dword v15, v41, s[4:5]
	s_mov_b64 exec, s[20:21]
	v_mov_b32_e32 v38, v27
	v_cmp_gt_u32_e32 vcc, 0x70000, v38
	s_mov_b64 s[14:15], vcc
	v_lshrrev_b32_e32 v39, 6, v38
	s_mov_b32 s22, 0x124924a
	v_mul_hi_u32 v40, v39, s22
	v_mul_u32_u24_e32 v39, 0xe0, v40
	v_lshrrev_b32_e32 v42, 6, v38
	v_sub_u32_e32 v39, v42, v39
	v_bfe_u32 v42, v38, 4, 2
	v_lshl_add_u32 v42, v40, 2, v42
	v_and_b32_e32 v40, 15, v38
	v_lshl_add_u32 v40, v39, 4, v40
	v_mov_b32_e32 v39, v42
	v_mul_u32_u24_e32 v41, 0x37400, v39
	v_lshl_add_u32 v41, v40, 2, v41
	v_add_u32_e32 v41, 0x3680, v41
	v_lshlrev_b32_e32 v36, 11, v40
	v_lshl_add_u32 v36, v39, 4, v36
	v_add_u32_e32 v36, 0xb00000, v36
	s_mov_b64 exec, s[14:15]
	global_load_dword v16, v41, s[4:5]
	v_add_u32_e32 v41, 0x6e80, v41
	global_load_dword v17, v41, s[4:5]
	v_add_u32_e32 v41, 0x6e80, v41
	global_load_dword v18, v41, s[4:5]
	v_add_u32_e32 v41, 0x6e80, v41
	global_load_dword v19, v41, s[4:5]
	v_add_u32_e32 v41, 0x6e80, v41
	global_load_dword v20, v41, s[4:5]
	v_add_u32_e32 v41, 0x6e80, v41
	global_load_dword v21, v41, s[4:5]
	v_add_u32_e32 v41, 0x6e80, v41
	global_load_dword v22, v41, s[4:5]
	v_add_u32_e32 v41, 0x6e80, v41
	global_load_dword v23, v41, s[4:5]
	s_mov_b64 exec, s[20:21]
	s_mul_i32 s0, s76, 1
	v_add_u32_e32 v38, s0, v27
	v_cmp_gt_u32_e32 vcc, 0x70000, v38
	s_mov_b64 s[16:17], vcc
	v_lshrrev_b32_e32 v39, 6, v38
	s_mov_b32 s22, 0x124924a
	v_mul_hi_u32 v40, v39, s22
	v_mul_u32_u24_e32 v39, 0xe0, v40
	v_lshrrev_b32_e32 v42, 6, v38
	v_sub_u32_e32 v39, v42, v39
	v_bfe_u32 v42, v38, 4, 2
	v_lshl_add_u32 v42, v40, 2, v42
	v_and_b32_e32 v40, 15, v38
	v_lshl_add_u32 v40, v39, 4, v40
	v_mov_b32_e32 v39, v42
	v_mul_u32_u24_e32 v41, 0x37400, v39
	v_lshl_add_u32 v41, v40, 2, v41
	v_add_u32_e32 v41, 0x3680, v41
	v_lshlrev_b32_e32 v37, 11, v40
	v_lshl_add_u32 v37, v39, 4, v37
	v_add_u32_e32 v37, 0xb00000, v37
	s_mov_b64 exec, s[16:17]
	global_load_dword v28, v41, s[4:5]
	v_add_u32_e32 v41, 0x6e80, v41
	global_load_dword v29, v41, s[4:5]
	v_add_u32_e32 v41, 0x6e80, v41
	global_load_dword v30, v41, s[4:5]
	v_add_u32_e32 v41, 0x6e80, v41
	global_load_dword v31, v41, s[4:5]
	v_add_u32_e32 v41, 0x6e80, v41
	global_load_dword v32, v41, s[4:5]
	v_add_u32_e32 v41, 0x6e80, v41
	global_load_dword v33, v41, s[4:5]
	v_add_u32_e32 v41, 0x6e80, v41
	global_load_dword v34, v41, s[4:5]
	v_add_u32_e32 v41, 0x6e80, v41
	global_load_dword v35, v41, s[4:5]
	s_mov_b64 exec, s[20:21]
	s_waitcnt vmcnt(0)
	s_mov_b64 exec, s[10:11]
	v_cvt_pk_bf16_f32 v0, v0, v1
	v_cvt_pk_bf16_f32 v1, v2, v3
	v_cvt_pk_bf16_f32 v2, v4, v5
	v_cvt_pk_bf16_f32 v3, v6, v7
	global_store_dwordx4 v24, v[0:3], s[2:3]
	s_mov_b64 exec, s[20:21]
	s_mov_b64 exec, s[12:13]
	v_cvt_pk_bf16_f32 v8, v8, v9
	v_cvt_pk_bf16_f32 v9, v10, v11
	v_cvt_pk_bf16_f32 v10, v12, v13
	v_cvt_pk_bf16_f32 v11, v14, v15
	global_store_dwordx4 v25, v[8:11], s[2:3]
	s_mov_b64 exec, s[20:21]
	s_mov_b64 exec, s[14:15]
	v_cvt_pk_bf16_f32 v16, v16, v17
	v_cvt_pk_bf16_f32 v17, v18, v19
	v_cvt_pk_bf16_f32 v18, v20, v21
	v_cvt_pk_bf16_f32 v19, v22, v23
	global_store_dwordx4 v36, v[16:19], s[2:3]
	s_mov_b64 exec, s[20:21]
	s_mov_b64 exec, s[16:17]
	v_cvt_pk_bf16_f32 v28, v28, v29
	v_cvt_pk_bf16_f32 v29, v30, v31
	v_cvt_pk_bf16_f32 v30, v32, v33
	v_cvt_pk_bf16_f32 v31, v34, v35
	global_store_dwordx4 v37, v[28:31], s[2:3]
	s_mov_b64 exec, s[20:21]
	s_mul_i32 s0, s76, 2
	v_add_u32_e32 v38, s0, v27
	v_cmp_gt_u32_e32 vcc, 0x6d000, v38
	s_mov_b64 s[10:11], vcc
	v_lshrrev_b32_e32 v39, 6, v38
	s_mov_b32 s22, 0x12c9fb5
	v_mul_hi_u32 v40, v39, s22
	v_mul_u32_u24_e32 v39, 0xda, v40
	v_lshrrev_b32_e32 v42, 6, v38
	v_sub_u32_e32 v39, v42, v39
	v_bfe_u32 v42, v38, 4, 2
	v_lshl_add_u32 v42, v40, 2, v42
	v_and_b32_e32 v40, 15, v38
	v_lshl_add_u32 v40, v39, 4, v40
	v_mov_b32_e32 v39, v42
	v_mul_u32_u24_e32 v41, 0x37400, v39
	v_lshl_add_u32 v41, v40, 2, v41
	v_lshlrev_b32_e32 v24, 11, v40
	v_lshl_add_u32 v24, v39, 4, v24
	v_add_u32_e32 v24, 0x400000, v24
	s_mov_b64 exec, s[10:11]
	global_load_dword v0, v41, s[4:5]
	v_add_u32_e32 v41, 0x6e80, v41
	global_load_dword v1, v41, s[4:5]
	v_add_u32_e32 v41, 0x6e80, v41
	global_load_dword v2, v41, s[4:5]
	v_add_u32_e32 v41, 0x6e80, v41
	global_load_dword v3, v41, s[4:5]
	v_add_u32_e32 v41, 0x6e80, v41
	global_load_dword v4, v41, s[4:5]
	v_add_u32_e32 v41, 0x6e80, v41
	global_load_dword v5, v41, s[4:5]
	v_add_u32_e32 v41, 0x6e80, v41
	global_load_dword v6, v41, s[4:5]
	v_add_u32_e32 v41, 0x6e80, v41
	global_load_dword v7, v41, s[4:5]
	s_mov_b64 exec, s[20:21]
	s_mul_i32 s0, s76, 3
	v_add_u32_e32 v38, s0, v27
	v_cmp_gt_u32_e32 vcc, 0x6d000, v38
	s_mov_b64 s[12:13], vcc
	v_lshrrev_b32_e32 v39, 6, v38
	s_mov_b32 s22, 0x12c9fb5
	v_mul_hi_u32 v40, v39, s22
	v_mul_u32_u24_e32 v39, 0xda, v40
	v_lshrrev_b32_e32 v42, 6, v38
	v_sub_u32_e32 v39, v42, v39
	v_bfe_u32 v42, v38, 4, 2
	v_lshl_add_u32 v42, v40, 2, v42
	v_and_b32_e32 v40, 15, v38
	v_lshl_add_u32 v40, v39, 4, v40
	v_mov_b32_e32 v39, v42
	v_mul_u32_u24_e32 v41, 0x37400, v39
	v_lshl_add_u32 v41, v40, 2, v41
	v_lshlrev_b32_e32 v25, 11, v40
	v_lshl_add_u32 v25, v39, 4, v25
	v_add_u32_e32 v25, 0x400000, v25
	s_mov_b64 exec, s[12:13]
	global_load_dword v8, v41, s[4:5]
	v_add_u32_e32 v41, 0x6e80, v41
	global_load_dword v9, v41, s[4:5]
	v_add_u32_e32 v41, 0x6e80, v41
	global_load_dword v10, v41, s[4:5]
	v_add_u32_e32 v41, 0x6e80, v41
	global_load_dword v11, v41, s[4:5]
	v_add_u32_e32 v41, 0x6e80, v41
	global_load_dword v12, v41, s[4:5]
	v_add_u32_e32 v41, 0x6e80, v41
	global_load_dword v13, v41, s[4:5]
	v_add_u32_e32 v41, 0x6e80, v41
	global_load_dword v14, v41, s[4:5]
	v_add_u32_e32 v41, 0x6e80, v41
	global_load_dword v15, v41, s[4:5]
	s_mov_b64 exec, s[20:21]
	s_mul_i32 s0, s76, 2
	v_add_u32_e32 v38, s0, v27
	v_cmp_gt_u32_e32 vcc, 0x70000, v38
	s_mov_b64 s[14:15], vcc
	v_lshrrev_b32_e32 v39, 6, v38
	s_mov_b32 s22, 0x124924a
	v_mul_hi_u32 v40, v39, s22
	v_mul_u32_u24_e32 v39, 0xe0, v40
	v_lshrrev_b32_e32 v42, 6, v38
	v_sub_u32_e32 v39, v42, v39
	v_bfe_u32 v42, v38, 4, 2
	v_lshl_add_u32 v42, v40, 2, v42
	v_and_b32_e32 v40, 15, v38
	v_lshl_add_u32 v40, v39, 4, v40
	v_mov_b32_e32 v39, v42
	v_mul_u32_u24_e32 v41, 0x37400, v39
	v_lshl_add_u32 v41, v40, 2, v41
	v_add_u32_e32 v41, 0x3680, v41
	v_lshlrev_b32_e32 v36, 11, v40
	v_lshl_add_u32 v36, v39, 4, v36
	v_add_u32_e32 v36, 0xb00000, v36
	s_mov_b64 exec, s[14:15]
	global_load_dword v16, v41, s[4:5]
	v_add_u32_e32 v41, 0x6e80, v41
	global_load_dword v17, v41, s[4:5]
	v_add_u32_e32 v41, 0x6e80, v41
	global_load_dword v18, v41, s[4:5]
	v_add_u32_e32 v41, 0x6e80, v41
	global_load_dword v19, v41, s[4:5]
	v_add_u32_e32 v41, 0x6e80, v41
	global_load_dword v20, v41, s[4:5]
	v_add_u32_e32 v41, 0x6e80, v41
	global_load_dword v21, v41, s[4:5]
	v_add_u32_e32 v41, 0x6e80, v41
	global_load_dword v22, v41, s[4:5]
	v_add_u32_e32 v41, 0x6e80, v41
	global_load_dword v23, v41, s[4:5]
	s_mov_b64 exec, s[20:21]
	s_mul_i32 s0, s76, 3
	v_add_u32_e32 v38, s0, v27
	v_cmp_gt_u32_e32 vcc, 0x70000, v38
	s_mov_b64 s[16:17], vcc
	v_lshrrev_b32_e32 v39, 6, v38
	s_mov_b32 s22, 0x124924a
	v_mul_hi_u32 v40, v39, s22
	v_mul_u32_u24_e32 v39, 0xe0, v40
	v_lshrrev_b32_e32 v42, 6, v38
	v_sub_u32_e32 v39, v42, v39
	v_bfe_u32 v42, v38, 4, 2
	v_lshl_add_u32 v42, v40, 2, v42
	v_and_b32_e32 v40, 15, v38
	v_lshl_add_u32 v40, v39, 4, v40
	v_mov_b32_e32 v39, v42
	v_mul_u32_u24_e32 v41, 0x37400, v39
	v_lshl_add_u32 v41, v40, 2, v41
	v_add_u32_e32 v41, 0x3680, v41
	v_lshlrev_b32_e32 v37, 11, v40
	v_lshl_add_u32 v37, v39, 4, v37
	v_add_u32_e32 v37, 0xb00000, v37
	s_mov_b64 exec, s[16:17]
	global_load_dword v28, v41, s[4:5]
	v_add_u32_e32 v41, 0x6e80, v41
	global_load_dword v29, v41, s[4:5]
	v_add_u32_e32 v41, 0x6e80, v41
	global_load_dword v30, v41, s[4:5]
	v_add_u32_e32 v41, 0x6e80, v41
	global_load_dword v31, v41, s[4:5]
	v_add_u32_e32 v41, 0x6e80, v41
	global_load_dword v32, v41, s[4:5]
	v_add_u32_e32 v41, 0x6e80, v41
	global_load_dword v33, v41, s[4:5]
	v_add_u32_e32 v41, 0x6e80, v41
	global_load_dword v34, v41, s[4:5]
	v_add_u32_e32 v41, 0x6e80, v41
	global_load_dword v35, v41, s[4:5]
	s_mov_b64 exec, s[20:21]
	s_waitcnt vmcnt(0)
	s_mov_b64 exec, s[10:11]
	v_cvt_pk_bf16_f32 v0, v0, v1
	v_cvt_pk_bf16_f32 v1, v2, v3
	v_cvt_pk_bf16_f32 v2, v4, v5
	v_cvt_pk_bf16_f32 v3, v6, v7
	global_store_dwordx4 v24, v[0:3], s[2:3]
	s_mov_b64 exec, s[20:21]
	s_mov_b64 exec, s[12:13]
	v_cvt_pk_bf16_f32 v8, v8, v9
	v_cvt_pk_bf16_f32 v9, v10, v11
	v_cvt_pk_bf16_f32 v10, v12, v13
	v_cvt_pk_bf16_f32 v11, v14, v15
	global_store_dwordx4 v25, v[8:11], s[2:3]
	s_mov_b64 exec, s[20:21]
	s_mov_b64 exec, s[14:15]
	v_cvt_pk_bf16_f32 v16, v16, v17
	v_cvt_pk_bf16_f32 v17, v18, v19
	v_cvt_pk_bf16_f32 v18, v20, v21
	v_cvt_pk_bf16_f32 v19, v22, v23
	global_store_dwordx4 v36, v[16:19], s[2:3]
	s_mov_b64 exec, s[20:21]
	s_mov_b64 exec, s[16:17]
	v_cvt_pk_bf16_f32 v28, v28, v29
	v_cvt_pk_bf16_f32 v29, v30, v31
	v_cvt_pk_bf16_f32 v30, v32, v33
	v_cvt_pk_bf16_f32 v31, v34, v35
	global_store_dwordx4 v37, v[28:31], s[2:3]
	s_mov_b64 exec, s[20:21]
	v_readlane_b32 s4, v253, 34
	v_readlane_b32 s5, v253, 35
	v_readlane_b32 s14, v253, 32
	v_readlane_b32 s15, v253, 33
	s_nop 1
	s_mul_i32 s0, s23, 0x80000
	s_add_u32 s4, s4, s0
	s_addc_u32 s5, s5, 0
	s_lshl_b32 s0, s23, 9
	s_add_u32 s14, s14, s0
	s_addc_u32 s15, s15, 0
	v_mov_b32_e32 v38, v27
	v_cmp_gt_u32_e32 vcc, 0x6000, v38
	s_mov_b64 s[10:11], vcc
	v_lshrrev_b32_e32 v39, 6, v38
	s_mov_b32 s22, 0x5555556
	v_mul_hi_u32 v40, v39, s22
	v_mul_u32_u24_e32 v39, 0x30, v40
	v_lshrrev_b32_e32 v42, 6, v38
	v_sub_u32_e32 v39, v42, v39
	v_bfe_u32 v42, v38, 4, 2
	v_lshl_add_u32 v42, v40, 2, v42
	v_and_b32_e32 v40, 15, v38
	v_lshl_add_u32 v40, v39, 4, v40
	v_mov_b32_e32 v39, v42
	v_mul_u32_u24_e32 v41, 0x6000, v39
	v_lshl_add_u32 v41, v40, 2, v41
	v_lshlrev_b32_e32 v24, 9, v40
	v_lshl_add_u32 v24, v39, 4, v24
	v_add_u32_e32 v24, 0x1200000, v24
	v_lshlrev_b32_e32 v42, 5, v39
	s_mov_b64 exec, s[10:11]
	global_load_dword v0, v41, s[6:7]
	v_add_u32_e32 v41, 0xc00, v41
	global_load_dword v1, v41, s[6:7]
	v_add_u32_e32 v41, 0xc00, v41
	global_load_dword v2, v41, s[6:7]
	v_add_u32_e32 v41, 0xc00, v41
	global_load_dword v3, v41, s[6:7]
	v_add_u32_e32 v41, 0xc00, v41
	global_load_dword v4, v41, s[6:7]
	v_add_u32_e32 v41, 0xc00, v41
	global_load_dword v5, v41, s[6:7]
	v_add_u32_e32 v41, 0xc00, v41
	global_load_dword v6, v41, s[6:7]
	v_add_u32_e32 v41, 0xc00, v41
	global_load_dword v7, v41, s[6:7]
	global_load_dwordx4 v[8:11], v42, s[8:9]
	global_load_dwordx4 v[12:15], v42, s[8:9] offset:16
	s_mov_b64 exec, s[20:21]
	v_mov_b32_e32 v38, v27
	v_cmp_gt_u32_e32 vcc, 0x4000, v38
	s_mov_b64 s[12:13], vcc
	v_lshrrev_b32_e32 v39, 6, v38
	v_lshrrev_b32_e32 v40, 12, v38
	v_lshlrev_b32_e32 v39, 6, v40
	v_lshrrev_b32_e32 v42, 6, v38
	v_sub_u32_e32 v39, v42, v39
	v_bfe_u32 v42, v38, 4, 2
	v_lshl_add_u32 v42, v40, 2, v42
	v_and_b32_e32 v40, 15, v38
	v_lshl_add_u32 v40, v39, 4, v40
	v_mov_b32_e32 v39, v42
	v_mul_u32_u24_e32 v41, 0x8000, v39
	v_lshl_add_u32 v41, v40, 2, v41
	v_lshlrev_b32_e32 v25, 8, v40
	v_lshl_add_u32 v25, v39, 4, v25
	v_add_u32_e32 v25, 0x1280000, v25
	v_lshlrev_b32_e32 v42, 5, v39
	s_mov_b64 exec, s[12:13]
	global_load_dword v16, v41, s[4:5]
	v_add_u32_e32 v41, 0x1000, v41
	global_load_dword v17, v41, s[4:5]
	v_add_u32_e32 v41, 0x1000, v41
	global_load_dword v18, v41, s[4:5]
	v_add_u32_e32 v41, 0x1000, v41
	global_load_dword v19, v41, s[4:5]
	v_add_u32_e32 v41, 0x1000, v41
	global_load_dword v20, v41, s[4:5]
	v_add_u32_e32 v41, 0x1000, v41
	global_load_dword v21, v41, s[4:5]
	v_add_u32_e32 v41, 0x1000, v41
	global_load_dword v22, v41, s[4:5]
	v_add_u32_e32 v41, 0x1000, v41
	global_load_dword v23, v41, s[4:5]
	global_load_dwordx4 v[28:31], v42, s[14:15]
	global_load_dwordx4 v[32:35], v42, s[14:15] offset:16
	s_mov_b64 exec, s[20:21]
	s_waitcnt vmcnt(0)
	s_mov_b64 exec, s[10:11]
	v_mul_f32_e32 v0, v0, v8
	v_mul_f32_e32 v1, v1, v9
	v_mul_f32_e32 v2, v2, v10
	v_mul_f32_e32 v3, v3, v11
	v_mul_f32_e32 v4, v4, v12
	v_mul_f32_e32 v5, v5, v13
	v_mul_f32_e32 v6, v6, v14
	v_mul_f32_e32 v7, v7, v15
	v_cvt_pk_bf16_f32 v0, v0, v1
	v_cvt_pk_bf16_f32 v1, v2, v3
	v_cvt_pk_bf16_f32 v2, v4, v5
	v_cvt_pk_bf16_f32 v3, v6, v7
	global_store_dwordx4 v24, v[0:3], s[2:3]
	s_mov_b64 exec, s[20:21]
	s_mov_b64 exec, s[12:13]
	v_mul_f32_e32 v16, v16, v28
	v_mul_f32_e32 v17, v17, v29
	v_mul_f32_e32 v18, v18, v30
	v_mul_f32_e32 v19, v19, v31
	v_mul_f32_e32 v20, v20, v32
	v_mul_f32_e32 v21, v21, v33
	v_mul_f32_e32 v22, v22, v34
	v_mul_f32_e32 v23, v23, v35
	v_cvt_pk_bf16_f32 v16, v16, v17
	v_cvt_pk_bf16_f32 v17, v18, v19
	v_cvt_pk_bf16_f32 v18, v20, v21
	v_cvt_pk_bf16_f32 v19, v22, v23
	global_store_dwordx4 v25, v[16:19], s[2:3]
	s_mov_b64 exec, s[20:21]
	v_cmp_gt_u32_e32 vcc, 0x3000, v27
	v_lshlrev_b32_e32 v38, 4, v27
	v_add_u32_e32 v38, 0xad0000, v38
	v_mov_b32_e32 v0, 0
	v_mov_b32_e32 v1, 0
	v_mov_b32_e32 v2, 0
	v_mov_b32_e32 v3, 0
	s_and_b64 exec, s[20:21], vcc
	global_store_dwordx4 v38, v[0:3], s[2:3]
	s_mov_b64 exec, s[20:21]
	.p2align 6
	s_nop 0
	s_nop 0
	s_nop 0
	s_nop 0
	s_nop 0
	s_nop 0

.LBB0_806:
	s_lshr_b32 s0, s71, 3
	s_cmp_lt_u32 s0, 8
	s_cbranch_scc1 .Lp5conv_skip
	v_readlane_b32 s23, v255, 29
	v_readlane_b32 s0, v253, 48
	s_nop 1
	s_cmp_ge_u32 s23, 4
	s_cbranch_scc1 .Lp5conv_skip
	s_mov_b64 s[20:21], exec
	v_readlane_b32 s2, v253, 2
	v_readlane_b32 s3, v253, 3
	v_readlane_b32 s4, v253, 20
	v_readlane_b32 s5, v253, 21
	v_readlane_b32 s6, v253, 30
	v_readlane_b32 s7, v253, 31
	v_readlane_b32 s8, v253, 28
	v_readlane_b32 s9, v253, 29
	s_sub_i32 s0, s0, 0x1000
	v_add_u32_e32 v27, s0, v170
	s_mul_hi_u32 s1, s23, 0x1ba0000
	s_mul_i32 s0, s23, 0x1ba0000
	s_add_u32 s4, s4, s0
	s_addc_u32 s5, s5, s1
	s_mul_i32 s0, s23, 0xc0000
	s_add_u32 s6, s6, s0
	s_addc_u32 s7, s7, 0
	s_lshl_b32 s0, s23, 10
	s_add_u32 s8, s8, s0
	s_addc_u32 s9, s9, 0
	v_mov_b32_e32 v38, v27
	v_cmp_gt_u32_e32 vcc, 0x6d000, v38
	s_mov_b64 s[10:11], vcc
	v_lshrrev_b32_e32 v39, 6, v38
	s_mov_b32 s22, 0x12c9fb5
	v_mul_hi_u32 v40, v39, s22
	v_mul_u32_u24_e32 v39, 0xda, v40
	v_lshrrev_b32_e32 v42, 6, v38
	v_sub_u32_e32 v39, v42, v39
	v_bfe_u32 v42, v38, 4, 2
	v_lshl_add_u32 v42, v40, 2, v42
	v_and_b32_e32 v40, 15, v38
	v_lshl_add_u32 v40, v39, 4, v40
	v_mov_b32_e32 v39, v42
	v_mul_u32_u24_e32 v41, 0x37400, v39
	v_lshl_add_u32 v41, v40, 2, v41
	v_lshlrev_b32_e32 v24, 11, v40
	v_lshl_add_u32 v24, v39, 4, v24
	v_add_u32_e32 v24, 0x400000, v24
	s_mov_b64 exec, s[10:11]
	global_load_dword v0, v41, s[4:5]
	v_add_u32_e32 v41, 0x6e80, v41
	global_load_dword v1, v41, s[4:5]
	v_add_u32_e32 v41, 0x6e80, v41
	global_load_dword v2, v41, s[4:5]
	v_add_u32_e32 v41, 0x6e80, v41
	global_load_dword v3, v41, s[4:5]
	v_add_u32_e32 v41, 0x6e80, v41
	global_load_dword v4, v41, s[4:5]
	v_add_u32_e32 v41, 0x6e80, v41
	global_load_dword v5, v41, s[4:5]
	v_add_u32_e32 v41, 0x6e80, v41
	global_load_dword v6, v41, s[4:5]
	v_add_u32_e32 v41, 0x6e80, v41
	global_load_dword v7, v41, s[4:5]
	s_mov_b64 exec, s[20:21]
	s_mov_b32 s0, 0x1f000
	v_add_u32_e32 v38, s0, v27
	v_cmp_gt_u32_e32 vcc, 0x6d000, v38
	s_mov_b64 s[12:13], vcc
	v_lshrrev_b32_e32 v39, 6, v38
	s_mov_b32 s22, 0x12c9fb5
	v_mul_hi_u32 v40, v39, s22
	v_mul_u32_u24_e32 v39, 0xda, v40
	v_lshrrev_b32_e32 v42, 6, v38
	v_sub_u32_e32 v39, v42, v39
	v_bfe_u32 v42, v38, 4, 2
	v_lshl_add_u32 v42, v40, 2, v42
	v_and_b32_e32 v40, 15, v38
	v_lshl_add_u32 v40, v39, 4, v40
	v_mov_b32_e32 v39, v42
	v_mul_u32_u24_e32 v41, 0x37400, v39
	v_lshl_add_u32 v41, v40, 2, v41
	v_lshlrev_b32_e32 v25, 11, v40
	v_lshl_add_u32 v25, v39, 4, v25
	v_add_u32_e32 v25, 0x400000, v25
	s_mov_b64 exec, s[12:13]
	global_load_dword v8, v41, s[4:5]
	v_add_u32_e32 v41, 0x6e80, v41
	global_load_dword v9, v41, s[4:5]
	v_add_u32_e32 v41, 0x6e80, v41
	global_load_dword v10, v41, s[4:5]
	v_add_u32_e32 v41, 0x6e80, v41
	global_load_dword v11, v41, s[4:5]
	v_add_u32_e32 v41, 0x6e80, v41
	global_load_dword v12, v41, s[4:5]
	v_add_u32_e32 v41, 0x6e80, v41
	global_load_dword v13, v41, s[4:5]
	v_add_u32_e32 v41, 0x6e80, v41
	global_load_dword v14, v41, s[4:5]
	v_add_u32_e32 v41, 0x6e80, v41
	global_load_dword v15, v41, s[4:5]
	s_mov_b64 exec, s[20:21]
	v_mov_b32_e32 v38, v27
	v_cmp_gt_u32_e32 vcc, 0x70000, v38
	s_mov_b64 s[14:15], vcc
	v_lshrrev_b32_e32 v39, 6, v38
	s_mov_b32 s22, 0x124924a
	v_mul_hi_u32 v40, v39, s22
	v_mul_u32_u24_e32 v39, 0xe0, v40
	v_lshrrev_b32_e32 v42, 6, v38
	v_sub_u32_e32 v39, v42, v39
	v_bfe_u32 v42, v38, 4, 2
	v_lshl_add_u32 v42, v40, 2, v42
	v_and_b32_e32 v40, 15, v38
	v_lshl_add_u32 v40, v39, 4, v40
	v_mov_b32_e32 v39, v42
	v_mul_u32_u24_e32 v41, 0x37400, v39
	v_lshl_add_u32 v41, v40, 2, v41
	v_add_u32_e32 v41, 0x3680, v41
	v_lshlrev_b32_e32 v36, 11, v40
	v_lshl_add_u32 v36, v39, 4, v36
	v_add_u32_e32 v36, 0xb00000, v36
	s_mov_b64 exec, s[14:15]
	global_load_dword v16, v41, s[4:5]
	v_add_u32_e32 v41, 0x6e80, v41
	global_load_dword v17, v41, s[4:5]
	v_add_u32_e32 v41, 0x6e80, v41
	global_load_dword v18, v41, s[4:5]
	v_add_u32_e32 v41, 0x6e80, v41
	global_load_dword v19, v41, s[4:5]
	v_add_u32_e32 v41, 0x6e80, v41
	global_load_dword v20, v41, s[4:5]
	v_add_u32_e32 v41, 0x6e80, v41
	global_load_dword v21, v41, s[4:5]
	v_add_u32_e32 v41, 0x6e80, v41
	global_load_dword v22, v41, s[4:5]
	v_add_u32_e32 v41, 0x6e80, v41
	global_load_dword v23, v41, s[4:5]
	s_mov_b64 exec, s[20:21]
	s_mov_b32 s0, 0x1f000
	v_add_u32_e32 v38, s0, v27
	v_cmp_gt_u32_e32 vcc, 0x70000, v38
	s_mov_b64 s[16:17], vcc
	v_lshrrev_b32_e32 v39, 6, v38
	s_mov_b32 s22, 0x124924a
	v_mul_hi_u32 v40, v39, s22
	v_mul_u32_u24_e32 v39, 0xe0, v40
	v_lshrrev_b32_e32 v42, 6, v38
	v_sub_u32_e32 v39, v42, v39
	v_bfe_u32 v42, v38, 4, 2
	v_lshl_add_u32 v42, v40, 2, v42
	v_and_b32_e32 v40, 15, v38
	v_lshl_add_u32 v40, v39, 4, v40
	v_mov_b32_e32 v39, v42
	v_mul_u32_u24_e32 v41, 0x37400, v39
	v_lshl_add_u32 v41, v40, 2, v41
	v_add_u32_e32 v41, 0x3680, v41
	v_lshlrev_b32_e32 v37, 11, v40
	v_lshl_add_u32 v37, v39, 4, v37
	v_add_u32_e32 v37, 0xb00000, v37
	s_mov_b64 exec, s[16:17]
	global_load_dword v28, v41, s[4:5]
	v_add_u32_e32 v41, 0x6e80, v41
	global_load_dword v29, v41, s[4:5]
	v_add_u32_e32 v41, 0x6e80, v41
	global_load_dword v30, v41, s[4:5]
	v_add_u32_e32 v41, 0x6e80, v41
	global_load_dword v31, v41, s[4:5]
	v_add_u32_e32 v41, 0x6e80, v41
	global_load_dword v32, v41, s[4:5]
	v_add_u32_e32 v41, 0x6e80, v41
	global_load_dword v33, v41, s[4:5]
	v_add_u32_e32 v41, 0x6e80, v41
	global_load_dword v34, v41, s[4:5]
	v_add_u32_e32 v41, 0x6e80, v41
	global_load_dword v35, v41, s[4:5]
	s_mov_b64 exec, s[20:21]
	s_waitcnt vmcnt(0)
	s_mov_b64 exec, s[10:11]
	v_cvt_pk_bf16_f32 v0, v0, v1
	v_cvt_pk_bf16_f32 v1, v2, v3
	v_cvt_pk_bf16_f32 v2, v4, v5
	v_cvt_pk_bf16_f32 v3, v6, v7
	global_store_dwordx4 v24, v[0:3], s[2:3]
	s_mov_b64 exec, s[20:21]
	s_mov_b64 exec, s[12:13]
	v_cvt_pk_bf16_f32 v8, v8, v9
	v_cvt_pk_bf16_f32 v9, v10, v11
	v_cvt_pk_bf16_f32 v10, v12, v13
	v_cvt_pk_bf16_f32 v11, v14, v15
	global_store_dwordx4 v25, v[8:11], s[2:3]
	s_mov_b64 exec, s[20:21]
	s_mov_b64 exec, s[14:15]
	v_cvt_pk_bf16_f32 v16, v16, v17
	v_cvt_pk_bf16_f32 v17, v18, v19
	v_cvt_pk_bf16_f32 v18, v20, v21
	v_cvt_pk_bf16_f32 v19, v22, v23
	global_store_dwordx4 v36, v[16:19], s[2:3]
	s_mov_b64 exec, s[20:21]
	s_mov_b64 exec, s[16:17]
	v_cvt_pk_bf16_f32 v28, v28, v29
	v_cvt_pk_bf16_f32 v29, v30, v31
	v_cvt_pk_bf16_f32 v30, v32, v33
	v_cvt_pk_bf16_f32 v31, v34, v35
	global_store_dwordx4 v37, v[28:31], s[2:3]
	s_mov_b64 exec, s[20:21]
	s_mov_b32 s0, 0x3e000
	v_add_u32_e32 v38, s0, v27
	v_cmp_gt_u32_e32 vcc, 0x6d000, v38
	s_mov_b64 s[10:11], vcc
	v_lshrrev_b32_e32 v39, 6, v38
	s_mov_b32 s22, 0x12c9fb5
	v_mul_hi_u32 v40, v39, s22
	v_mul_u32_u24_e32 v39, 0xda, v40
	v_lshrrev_b32_e32 v42, 6, v38
	v_sub_u32_e32 v39, v42, v39
	v_bfe_u32 v42, v38, 4, 2
	v_lshl_add_u32 v42, v40, 2, v42
	v_and_b32_e32 v40, 15, v38
	v_lshl_add_u32 v40, v39, 4, v40
	v_mov_b32_e32 v39, v42
	v_mul_u32_u24_e32 v41, 0x37400, v39
	v_lshl_add_u32 v41, v40, 2, v41
	v_lshlrev_b32_e32 v24, 11, v40
	v_lshl_add_u32 v24, v39, 4, v24
	v_add_u32_e32 v24, 0x400000, v24
	s_mov_b64 exec, s[10:11]
	global_load_dword v0, v41, s[4:5]
	v_add_u32_e32 v41, 0x6e80, v41
	global_load_dword v1, v41, s[4:5]
	v_add_u32_e32 v41, 0x6e80, v41
	global_load_dword v2, v41, s[4:5]
	v_add_u32_e32 v41, 0x6e80, v41
	global_load_dword v3, v41, s[4:5]
	v_add_u32_e32 v41, 0x6e80, v41
	global_load_dword v4, v41, s[4:5]
	v_add_u32_e32 v41, 0x6e80, v41
	global_load_dword v5, v41, s[4:5]
	v_add_u32_e32 v41, 0x6e80, v41
	global_load_dword v6, v41, s[4:5]
	v_add_u32_e32 v41, 0x6e80, v41
	global_load_dword v7, v41, s[4:5]
	s_mov_b64 exec, s[20:21]
	s_mov_b32 s0, 0x5d000
	v_add_u32_e32 v38, s0, v27
	v_cmp_gt_u32_e32 vcc, 0x6d000, v38
	s_mov_b64 s[12:13], vcc
	v_lshrrev_b32_e32 v39, 6, v38
	s_mov_b32 s22, 0x12c9fb5
	v_mul_hi_u32 v40, v39, s22
	v_mul_u32_u24_e32 v39, 0xda, v40
	v_lshrrev_b32_e32 v42, 6, v38
	v_sub_u32_e32 v39, v42, v39
	v_bfe_u32 v42, v38, 4, 2
	v_lshl_add_u32 v42, v40, 2, v42
	v_and_b32_e32 v40, 15, v38
	v_lshl_add_u32 v40, v39, 4, v40
	v_mov_b32_e32 v39, v42
	v_mul_u32_u24_e32 v41, 0x37400, v39
	v_lshl_add_u32 v41, v40, 2, v41
	v_lshlrev_b32_e32 v25, 11, v40
	v_lshl_add_u32 v25, v39, 4, v25
	v_add_u32_e32 v25, 0x400000, v25
	s_mov_b64 exec, s[12:13]
	global_load_dword v8, v41, s[4:5]
	v_add_u32_e32 v41, 0x6e80, v41
	global_load_dword v9, v41, s[4:5]
	v_add_u32_e32 v41, 0x6e80, v41
	global_load_dword v10, v41, s[4:5]
	v_add_u32_e32 v41, 0x6e80, v41
	global_load_dword v11, v41, s[4:5]
	v_add_u32_e32 v41, 0x6e80, v41
	global_load_dword v12, v41, s[4:5]
	v_add_u32_e32 v41, 0x6e80, v41
	global_load_dword v13, v41, s[4:5]
	v_add_u32_e32 v41, 0x6e80, v41
	global_load_dword v14, v41, s[4:5]
	v_add_u32_e32 v41, 0x6e80, v41
	global_load_dword v15, v41, s[4:5]
	s_mov_b64 exec, s[20:21]
	s_mov_b32 s0, 0x3e000
	v_add_u32_e32 v38, s0, v27
	v_cmp_gt_u32_e32 vcc, 0x70000, v38
	s_mov_b64 s[14:15], vcc
	v_lshrrev_b32_e32 v39, 6, v38
	s_mov_b32 s22, 0x124924a
	v_mul_hi_u32 v40, v39, s22
	v_mul_u32_u24_e32 v39, 0xe0, v40
	v_lshrrev_b32_e32 v42, 6, v38
	v_sub_u32_e32 v39, v42, v39
	v_bfe_u32 v42, v38, 4, 2
	v_lshl_add_u32 v42, v40, 2, v42
	v_and_b32_e32 v40, 15, v38
	v_lshl_add_u32 v40, v39, 4, v40
	v_mov_b32_e32 v39, v42
	v_mul_u32_u24_e32 v41, 0x37400, v39
	v_lshl_add_u32 v41, v40, 2, v41
	v_add_u32_e32 v41, 0x3680, v41
	v_lshlrev_b32_e32 v36, 11, v40
	v_lshl_add_u32 v36, v39, 4, v36
	v_add_u32_e32 v36, 0xb00000, v36
	s_mov_b64 exec, s[14:15]
	global_load_dword v16, v41, s[4:5]
	v_add_u32_e32 v41, 0x6e80, v41
	global_load_dword v17, v41, s[4:5]
	v_add_u32_e32 v41, 0x6e80, v41
	global_load_dword v18, v41, s[4:5]
	v_add_u32_e32 v41, 0x6e80, v41
	global_load_dword v19, v41, s[4:5]
	v_add_u32_e32 v41, 0x6e80, v41
	global_load_dword v20, v41, s[4:5]
	v_add_u32_e32 v41, 0x6e80, v41
	global_load_dword v21, v41, s[4:5]
	v_add_u32_e32 v41, 0x6e80, v41
	global_load_dword v22, v41, s[4:5]
	v_add_u32_e32 v41, 0x6e80, v41
	global_load_dword v23, v41, s[4:5]
	s_mov_b64 exec, s[20:21]
	s_mov_b32 s0, 0x5d000
	v_add_u32_e32 v38, s0, v27
	v_cmp_gt_u32_e32 vcc, 0x70000, v38
	s_mov_b64 s[16:17], vcc
	v_lshrrev_b32_e32 v39, 6, v38
	s_mov_b32 s22, 0x124924a
	v_mul_hi_u32 v40, v39, s22
	v_mul_u32_u24_e32 v39, 0xe0, v40
	v_lshrrev_b32_e32 v42, 6, v38
	v_sub_u32_e32 v39, v42, v39
	v_bfe_u32 v42, v38, 4, 2
	v_lshl_add_u32 v42, v40, 2, v42
	v_and_b32_e32 v40, 15, v38
	v_lshl_add_u32 v40, v39, 4, v40
	v_mov_b32_e32 v39, v42
	v_mul_u32_u24_e32 v41, 0x37400, v39
	v_lshl_add_u32 v41, v40, 2, v41
	v_add_u32_e32 v41, 0x3680, v41
	v_lshlrev_b32_e32 v37, 11, v40
	v_lshl_add_u32 v37, v39, 4, v37
	v_add_u32_e32 v37, 0xb00000, v37
	s_mov_b64 exec, s[16:17]
	global_load_dword v28, v41, s[4:5]
	v_add_u32_e32 v41, 0x6e80, v41
	global_load_dword v29, v41, s[4:5]
	v_add_u32_e32 v41, 0x6e80, v41
	global_load_dword v30, v41, s[4:5]
	v_add_u32_e32 v41, 0x6e80, v41
	global_load_dword v31, v41, s[4:5]
	v_add_u32_e32 v41, 0x6e80, v41
	global_load_dword v32, v41, s[4:5]
	v_add_u32_e32 v41, 0x6e80, v41
	global_load_dword v33, v41, s[4:5]
	v_add_u32_e32 v41, 0x6e80, v41
	global_load_dword v34, v41, s[4:5]
	v_add_u32_e32 v41, 0x6e80, v41
	global_load_dword v35, v41, s[4:5]
	s_mov_b64 exec, s[20:21]
	s_waitcnt vmcnt(0)
	s_mov_b64 exec, s[10:11]
	v_cvt_pk_bf16_f32 v0, v0, v1
	v_cvt_pk_bf16_f32 v1, v2, v3
	v_cvt_pk_bf16_f32 v2, v4, v5
	v_cvt_pk_bf16_f32 v3, v6, v7
	global_store_dwordx4 v24, v[0:3], s[2:3]
	s_mov_b64 exec, s[20:21]
	s_mov_b64 exec, s[12:13]
	v_cvt_pk_bf16_f32 v8, v8, v9
	v_cvt_pk_bf16_f32 v9, v10, v11
	v_cvt_pk_bf16_f32 v10, v12, v13
	v_cvt_pk_bf16_f32 v11, v14, v15
	global_store_dwordx4 v25, v[8:11], s[2:3]
	s_mov_b64 exec, s[20:21]
	s_mov_b64 exec, s[14:15]
	v_cvt_pk_bf16_f32 v16, v16, v17
	v_cvt_pk_bf16_f32 v17, v18, v19
	v_cvt_pk_bf16_f32 v18, v20, v21
	v_cvt_pk_bf16_f32 v19, v22, v23
	global_store_dwordx4 v36, v[16:19], s[2:3]
	s_mov_b64 exec, s[20:21]
	s_mov_b64 exec, s[16:17]
	v_cvt_pk_bf16_f32 v28, v28, v29
	v_cvt_pk_bf16_f32 v29, v30, v31
	v_cvt_pk_bf16_f32 v30, v32, v33
	v_cvt_pk_bf16_f32 v31, v34, v35
	global_store_dwordx4 v37, v[28:31], s[2:3]
	s_mov_b64 exec, s[20:21]
	v_readlane_b32 s4, v253, 34
	v_readlane_b32 s5, v253, 35
	v_readlane_b32 s14, v253, 32
	v_readlane_b32 s15, v253, 33
	s_nop 1
	s_mul_i32 s0, s23, 0x80000
	s_add_u32 s4, s4, s0
	s_addc_u32 s5, s5, 0
	s_lshl_b32 s0, s23, 9
	s_add_u32 s14, s14, s0
	s_addc_u32 s15, s15, 0
	v_mov_b32_e32 v38, v27
	v_cmp_gt_u32_e32 vcc, 0x6000, v38
	s_mov_b64 s[10:11], vcc
	v_lshrrev_b32_e32 v39, 6, v38
	s_mov_b32 s22, 0x5555556
	v_mul_hi_u32 v40, v39, s22
	v_mul_u32_u24_e32 v39, 0x30, v40
	v_lshrrev_b32_e32 v42, 6, v38
	v_sub_u32_e32 v39, v42, v39
	v_bfe_u32 v42, v38, 4, 2
	v_lshl_add_u32 v42, v40, 2, v42
	v_and_b32_e32 v40, 15, v38
	v_lshl_add_u32 v40, v39, 4, v40
	v_mov_b32_e32 v39, v42
	v_mul_u32_u24_e32 v41, 0x6000, v39
	v_lshl_add_u32 v41, v40, 2, v41
	v_lshlrev_b32_e32 v24, 9, v40
	v_lshl_add_u32 v24, v39, 4, v24
	v_add_u32_e32 v24, 0x1200000, v24
	v_lshlrev_b32_e32 v42, 5, v39
	s_mov_b64 exec, s[10:11]
	global_load_dword v0, v41, s[6:7]
	v_add_u32_e32 v41, 0xc00, v41
	global_load_dword v1, v41, s[6:7]
	v_add_u32_e32 v41, 0xc00, v41
	global_load_dword v2, v41, s[6:7]
	v_add_u32_e32 v41, 0xc00, v41
	global_load_dword v3, v41, s[6:7]
	v_add_u32_e32 v41, 0xc00, v41
	global_load_dword v4, v41, s[6:7]
	v_add_u32_e32 v41, 0xc00, v41
	global_load_dword v5, v41, s[6:7]
	v_add_u32_e32 v41, 0xc00, v41
	global_load_dword v6, v41, s[6:7]
	v_add_u32_e32 v41, 0xc00, v41
	global_load_dword v7, v41, s[6:7]
	global_load_dwordx4 v[8:11], v42, s[8:9]
	global_load_dwordx4 v[12:15], v42, s[8:9] offset:16
	s_mov_b64 exec, s[20:21]
	v_mov_b32_e32 v38, v27
	v_cmp_gt_u32_e32 vcc, 0x4000, v38
	s_mov_b64 s[12:13], vcc
	v_lshrrev_b32_e32 v39, 6, v38
	v_lshrrev_b32_e32 v40, 12, v38
	v_lshlrev_b32_e32 v39, 6, v40
	v_lshrrev_b32_e32 v42, 6, v38
	v_sub_u32_e32 v39, v42, v39
	v_bfe_u32 v42, v38, 4, 2
	v_lshl_add_u32 v42, v40, 2, v42
	v_and_b32_e32 v40, 15, v38
	v_lshl_add_u32 v40, v39, 4, v40
	v_mov_b32_e32 v39, v42
	v_mul_u32_u24_e32 v41, 0x8000, v39
	v_lshl_add_u32 v41, v40, 2, v41
	v_lshlrev_b32_e32 v25, 8, v40
	v_lshl_add_u32 v25, v39, 4, v25
	v_add_u32_e32 v25, 0x1280000, v25
	v_lshlrev_b32_e32 v42, 5, v39
	s_mov_b64 exec, s[12:13]
	global_load_dword v16, v41, s[4:5]
	v_add_u32_e32 v41, 0x1000, v41
	global_load_dword v17, v41, s[4:5]
	v_add_u32_e32 v41, 0x1000, v41
	global_load_dword v18, v41, s[4:5]
	v_add_u32_e32 v41, 0x1000, v41
	global_load_dword v19, v41, s[4:5]
	v_add_u32_e32 v41, 0x1000, v41
	global_load_dword v20, v41, s[4:5]
	v_add_u32_e32 v41, 0x1000, v41
	global_load_dword v21, v41, s[4:5]
	v_add_u32_e32 v41, 0x1000, v41
	global_load_dword v22, v41, s[4:5]
	v_add_u32_e32 v41, 0x1000, v41
	global_load_dword v23, v41, s[4:5]
	global_load_dwordx4 v[28:31], v42, s[14:15]
	global_load_dwordx4 v[32:35], v42, s[14:15] offset:16
	s_mov_b64 exec, s[20:21]
	s_waitcnt vmcnt(0)
	s_mov_b64 exec, s[10:11]
	v_mul_f32_e32 v0, v0, v8
	v_mul_f32_e32 v1, v1, v9
	v_mul_f32_e32 v2, v2, v10
	v_mul_f32_e32 v3, v3, v11
	v_mul_f32_e32 v4, v4, v12
	v_mul_f32_e32 v5, v5, v13
	v_mul_f32_e32 v6, v6, v14
	v_mul_f32_e32 v7, v7, v15
	v_cvt_pk_bf16_f32 v0, v0, v1
	v_cvt_pk_bf16_f32 v1, v2, v3
	v_cvt_pk_bf16_f32 v2, v4, v5
	v_cvt_pk_bf16_f32 v3, v6, v7
	global_store_dwordx4 v24, v[0:3], s[2:3]
	s_mov_b64 exec, s[20:21]
	s_mov_b64 exec, s[12:13]
	v_mul_f32_e32 v16, v16, v28
	v_mul_f32_e32 v17, v17, v29
	v_mul_f32_e32 v18, v18, v30
	v_mul_f32_e32 v19, v19, v31
	v_mul_f32_e32 v20, v20, v32
	v_mul_f32_e32 v21, v21, v33
	v_mul_f32_e32 v22, v22, v34
	v_mul_f32_e32 v23, v23, v35
	v_cvt_pk_bf16_f32 v16, v16, v17
	v_cvt_pk_bf16_f32 v17, v18, v19
	v_cvt_pk_bf16_f32 v18, v20, v21
	v_cvt_pk_bf16_f32 v19, v22, v23
	global_store_dwordx4 v25, v[16:19], s[2:3]
	s_mov_b64 exec, s[20:21]
	v_cmp_gt_u32_e32 vcc, 0x3000, v27
	v_lshlrev_b32_e32 v38, 4, v27
	v_add_u32_e32 v38, 0xad0000, v38
	v_mov_b32_e32 v0, 0
	v_mov_b32_e32 v1, 0
	v_mov_b32_e32 v2, 0
	v_mov_b32_e32 v3, 0
	s_and_b64 exec, s[20:21], vcc
	global_store_dwordx4 v38, v[0:3], s[2:3]
	s_mov_b64 exec, s[20:21]
